# speedup vs baseline: 1.0074x; 1.0074x over previous
; __device__ __forceinline__ f16v mfma16(h8 a, h8 b, f16v c) { return __builtin_amdgcn_mfma_f32_32x32x16_f16(a, b, c, 0, 0, 0); }
;   __device__ __forceinline__ float tile_c0(int kt, int qslot, int hi) const { return (float)(q0 + qslot - kt * 64 - 4 * hi); }
;   __device__ __forceinline__ float apply(float pv, float c0, int jc) const { return fmaf(-slope, fabsf(c0 - (float)jc), pv); }
;   __device__ __forceinline__ float tile_c0(int kt, int qslot, int hi) const { return (float)(qslot + 64 - 64 * kt - 4 * hi); }
; template <int EQK, int EV, bool PF, class KP, class SC>
; __device__ __forceinline__ void flash_core(f16v (&o)[EV / 32], float& m_run, float& l_run, const h8 (&qf)[EQK / 16],
;                                            int kt0, int kt1, const KP& kp, const SC& sc, char* smem) {
;     ...
;     if (!sc.wave_skip(kt, wid)) {
;       const h16* sK = base + (PF ? cur : 0) * BUFH;
;       const h16* sV = sK + 64 * KLD;
;       f16v p0, p1;
; #pragma unroll
;       for (int r = 0; r < 16; ++r) { p0[r] = 0.f; p1[r] = 0.f; }
; #pragma unroll
;       for (int d0 = 0; d0 < EQK / 16; ++d0) {
;         h8 a0 = *(const h8*)(sK + l31 * KLD + d0 * 16 + hi * 8);
;         h8 a1 = *(const h8*)(sK + (32 + l31) * KLD + d0 * 16 + hi * 8);
;         p0 = mfma16(a0, qf[d0], p0);
;         p1 = mfma16(a1, qf[d0], p1);
;       }
;       const float c0 = sc.tile_c0(kt, qslot, hi);
;       float mx = -1e30f;
; #pragma unroll
;       for (int r = 0; r < 16; ++r) {
;         const int jc = (r & 3) + 8 * (r >> 2);
;         p0[r] = sc.apply(p0[r], c0, jc);
;         p1[r] = sc.apply(p1[r], c0, 32 + jc);
;         mx = fmaxf(mx, fmaxf(p0[r], p1[r]));
;       }
.LBB0_1096:
	s_mul_i32 s41, s33, 0x6c00
	v_lshlrev_b32_e32 v189, 1, v143
	v_add3_u32 v0, s41, v189, v188
	ds_read_b128 v[2:5], v0
	ds_read_b128 v[6:9], v0 offset:32
	s_mov_b32 s3, 0xf149f2ca
	s_waitcnt lgkmcnt(1)
	v_mfma_f32_32x32x16_f16 v[80:95], v[2:5], v[124:127], 0
	ds_read_b128 v[2:5], v0 offset:4608
	ds_read_b128 v[10:13], v0 offset:4640
	v_mov_b32_e32 v195, v186
	s_waitcnt lgkmcnt(1)
	v_mfma_f32_32x32x16_f16 v[96:111], v[2:5], v[124:127], 0
	v_mfma_f32_32x32x16_f16 v[80:95], v[6:9], v[120:123], v[80:95]
	s_waitcnt lgkmcnt(0)
	v_mfma_f32_32x32x16_f16 v[96:111], v[10:13], v[120:123], v[96:111]
	ds_read_b128 v[2:5], v0 offset:64
	ds_read_b128 v[10:13], v0 offset:96
	s_waitcnt lgkmcnt(1)
	v_mfma_f32_32x32x16_f16 v[80:95], v[2:5], v[116:119], v[80:95]
	ds_read_b128 v[2:5], v0 offset:4672
	ds_read_b128 v[160:163], v0 offset:4704
	v_add_u32_e32 v0, s2, v187
	v_cvt_f32_i32_e32 v0, v0
	s_waitcnt lgkmcnt(1)
	v_mfma_f32_32x32x16_f16 v[96:111], v[2:5], v[116:119], v[96:111]
	global_load_dwordx4 v[6:9], v158, s[58:59]
	s_nop 0
	global_load_dwordx4 v[2:5], v156, s[58:59]
	s_waitcnt lgkmcnt(0)
	v_mfma_f32_32x32x16_f16 v[96:111], v[160:163], v[112:115], v[96:111]
	v_mfma_f32_32x32x16_f16 v[80:95], v[10:13], v[112:115], v[80:95]
	global_load_dwordx4 v[128:131], v154, s[58:59]
	s_nop 0
	global_load_dwordx4 v[10:13], v152, s[58:59]
	s_add_i32 vcc_lo, s2, s47
	s_cmp_gt_i32 vcc_lo, 63
	s_cbranch_scc1 .Lda1_left
	s_cmp_lt_i32 vcc_lo, 0xffffff81
	s_cbranch_scc1 .Lda1_right
	v_mov_b32_e32 v249, 0
	v_add_f32_e32 v15, 0xc2000000, v0
	s_nop 5
	v_fma_f32 v15, -v137, |v15|, v96
	v_add_f32_e32 v96, -1.0, v0
	v_fma_f32 v81, -v137, |v96|, v81
	v_add_f32_e32 v96, 0xc2040000, v0
	v_fma_f32 v14, -v137, |v0|, v80
	v_fma_f32 v96, -v137, |v96|, v97
	v_max_f32_e32 v80, v14, v15
	v_max_f32_e32 v97, v81, v96
	v_max3_f32 v80, v80, s3, v97
	v_add_f32_e32 v97, -2.0, v0
	v_fma_f32 v160, -v137, |v97|, v82
	v_add_f32_e32 v97, 0xc0400000, v0
	v_add_f32_e32 v82, 0xc2080000, v0
	v_fma_f32 v161, -v137, |v97|, v83
	v_add_f32_e32 v83, 0xc20c0000, v0
	v_fma_f32 v98, -v137, |v82|, v98
	v_fma_f32 v99, -v137, |v83|, v99
	v_max_f32_e32 v82, v160, v98
	v_max_f32_e32 v83, v161, v99
	v_max3_f32 v80, v80, v82, v83
	v_add_f32_e32 v82, 0xc1000000, v0
	v_add_f32_e32 v83, 0xc1100000, v0
	v_fma_f32 v162, -v137, |v82|, v84
	v_add_f32_e32 v82, 0xc2200000, v0
	v_fma_f32 v163, -v137, |v83|, v85
	v_add_f32_e32 v83, 0xc2240000, v0
	v_fma_f32 v100, -v137, |v82|, v100
	v_fma_f32 v101, -v137, |v83|, v101
	v_max_f32_e32 v82, v162, v100
	v_max_f32_e32 v83, v163, v101
	v_max3_f32 v80, v80, v82, v83
	v_add_f32_e32 v82, 0xc1200000, v0
	v_add_f32_e32 v83, 0xc1300000, v0
	v_fma_f32 v164, -v137, |v82|, v86
	v_add_f32_e32 v82, 0xc2280000, v0
	v_fma_f32 v166, -v137, |v83|, v87
	v_add_f32_e32 v83, 0xc22c0000, v0
	v_fma_f32 v165, -v137, |v82|, v102
	v_fma_f32 v167, -v137, |v83|, v103
	v_max_f32_e32 v82, v164, v165
	v_max_f32_e32 v83, v166, v167
	v_max3_f32 v80, v80, v82, v83
	v_add_f32_e32 v82, 0xc1800000, v0
	v_add_f32_e32 v83, 0xc1880000, v0
	v_fma_f32 v196, -v137, |v82|, v88
	v_add_f32_e32 v82, 0xc2400000, v0
	v_fma_f32 v197, -v137, |v83|, v89
	v_add_f32_e32 v83, 0xc2440000, v0
	v_fma_f32 v104, -v137, |v82|, v104
	v_fma_f32 v105, -v137, |v83|, v105
	v_max_f32_e32 v82, v196, v104
	v_max_f32_e32 v83, v197, v105
	v_max3_f32 v80, v80, v82, v83
	v_add_f32_e32 v82, 0xc1900000, v0
	v_add_f32_e32 v83, 0xc1980000, v0
	v_fma_f32 v198, -v137, |v82|, v90
	v_add_f32_e32 v82, 0xc2480000, v0
	v_fma_f32 v200, -v137, |v83|, v91
	v_add_f32_e32 v83, 0xc24c0000, v0
	v_fma_f32 v199, -v137, |v82|, v106
	v_fma_f32 v201, -v137, |v83|, v107
	v_max_f32_e32 v82, v198, v199
	v_max_f32_e32 v83, v200, v201
	v_max3_f32 v80, v80, v82, v83
	v_add_f32_e32 v82, 0xc1c00000, v0
	v_add_f32_e32 v83, 0xc1c80000, v0
	v_fma_f32 v202, -v137, |v82|, v92
	v_add_f32_e32 v82, 0xc2600000, v0
	v_fma_f32 v204, -v137, |v83|, v93
	v_add_f32_e32 v83, 0xc2640000, v0
	v_fma_f32 v203, -v137, |v82|, v108
	v_fma_f32 v205, -v137, |v83|, v109
	v_max_f32_e32 v82, v202, v203
	v_max_f32_e32 v83, v204, v205
	v_max3_f32 v80, v80, v82, v83
	v_add_f32_e32 v82, 0xc1d00000, v0
	v_fma_f32 v94, -v137, |v82|, v94
	v_add_f32_e32 v82, 0xc2680000, v0
	v_add_f32_e32 v83, 0xc1d80000, v0
	v_add_f32_e32 v0, 0xc26c0000, v0
	v_fma_f32 v206, -v137, |v82|, v110
	v_fma_f32 v207, -v137, |v83|, v95
	v_fma_f32 v208, -v137, |v0|, v111
	v_max_f32_e32 v82, v94, v206
	v_max_f32_e32 v0, v207, v208
	v_max3_f32 v0, v80, v82, v0
	s_branch .Lda1_join

; template <int EQK, int EV, bool PF, class KP, class SC>
; __device__ __forceinline__ void flash_core(f16v (&o)[EV / 32], float& m_run, float& l_run, const h8 (&qf)[EQK / 16],
;                                            int kt0, int kt1, const KP& kp, const SC& sc, char* smem) {
;     ...
;     for (int i = 0; i < NKC; ++i) { int c = tid + 256 * i, row = c / KCH, kc = (c - row * KCH) * 8; rk[i] = *(const h8*)(kp.kptr(kt, row) + kc); }
; #pragma unroll
;     for (int i = 0; i < NVC; ++i) { int c = tid + 256 * i, e = c >> 3, kc = (c & 7) * 8; rv[i] = *(const h8*)(kp.vptr(kt, e) + kc); }
;     ...
;       mx = xhalf_max(mx);
;       const float m_new = fmaxf(m_run, mx);
;       const float alpha = __builtin_amdgcn_exp2f((m_run - m_new) * L2E);
;       const float mneg = -m_new * L2E;
;       float ps = 0.f;
; #pragma unroll
;       for (int r = 0; r < 16; ++r) {
;         p0[r] = __builtin_amdgcn_exp2f(fmaf(p0[r], L2E, mneg));
;         p1[r] = __builtin_amdgcn_exp2f(fmaf(p1[r], L2E, mneg));
;         ps += p0[r] + p1[r];
;       }
;       ps = xhalf_sum(ps);
;       l_run = l_run * alpha + ps;
;       m_run = m_new;
;       if (__any(alpha != 1.f)) {
; #pragma unroll
;         for (int et = 0; et < EV / 32; ++et)
; #pragma unroll
;           for (int r = 0; r < 16; ++r) o[et][r] *= alpha;
;       }
.Lda1_join:
	v_add_f32_e32 v0, v249, v0
	v_mov_b32_e32 v80, v0
	s_nop 1
	v_permlane32_swap_b32_e32 v0, v80
	v_max3_f32 v186, v195, v0, v80
	v_sub_f32_e32 v209, v249, v186
	v_mul_f32_e32 v209, 0x3fb8aa3b, v209
	v_fmamk_f32 v0, v14, 0x3fb8aa3b, v209
	v_exp_f32_e32 v191, v0
	v_fmamk_f32 v0, v15, 0x3fb8aa3b, v209
	v_exp_f32_e32 v95, v0
	v_fmamk_f32 v0, v81, 0x3fb8aa3b, v209
	v_fmamk_f32 v14, v96, 0x3fb8aa3b, v209
	v_exp_f32_e32 v0, v0
	v_exp_f32_e32 v14, v14
	v_add_f32_e32 v15, v95, v191
	v_pk_add_f32 v[84:85], v[14:15], v[0:1]
	v_fmamk_f32 v15, v160, 0x3fb8aa3b, v209
	v_pk_add_f32 v[96:97], v[84:85], v[84:85] op_sel_hi:[0,1]
	v_fmamk_f32 v84, v161, 0x3fb8aa3b, v209
	v_exp_f32_e32 v96, v84
	v_fmamk_f32 v84, v99, 0x3fb8aa3b, v209
	v_exp_f32_e32 v88, v84
	global_load_dwordx4 v[84:87], v150, s[58:59]
	s_nop 0
	global_load_dwordx4 v[80:83], v148, s[58:59]
	v_exp_f32_e32 v192, v15
	v_fmamk_f32 v15, v98, 0x3fb8aa3b, v209
	v_exp_f32_e32 v15, v15
	s_nop 0
	v_add_f32_e32 v89, v15, v192
	v_pk_add_f32 v[90:91], v[88:89], v[96:97]
	v_fmamk_f32 v89, v162, 0x3fb8aa3b, v209
	v_pk_add_f32 v[102:103], v[90:91], v[90:91] op_sel_hi:[0,1]
	v_exp_f32_e32 v193, v89
	v_fmamk_f32 v89, v100, 0x3fb8aa3b, v209
	v_fmamk_f32 v90, v163, 0x3fb8aa3b, v209
	v_exp_f32_e32 v89, v89
	v_exp_f32_e32 v102, v90
	v_fmamk_f32 v90, v101, 0x3fb8aa3b, v209
	v_exp_f32_e32 v90, v90
	v_add_f32_e32 v91, v89, v193
	v_pk_add_f32 v[92:93], v[90:91], v[102:103]
	v_fmamk_f32 v91, v164, 0x3fb8aa3b, v209
	v_exp_f32_e32 v194, v91
	v_fmamk_f32 v91, v165, 0x3fb8aa3b, v209
	v_pk_add_f32 v[108:109], v[92:93], v[92:93] op_sel_hi:[0,1]
	v_exp_f32_e32 v103, v91
	v_fmamk_f32 v91, v166, 0x3fb8aa3b, v209
	v_exp_f32_e32 v108, v91
	v_fmamk_f32 v91, v167, 0x3fb8aa3b, v209
	v_exp_f32_e32 v100, v91
	v_add_f32_e32 v101, v103, v194
	v_fmamk_f32 v91, v196, 0x3fb8aa3b, v209
	v_pk_add_f32 v[92:93], v[100:101], v[108:109]
	v_exp_f32_e32 v101, v91
	v_fmamk_f32 v91, v104, 0x3fb8aa3b, v209
	v_pk_add_f32 v[106:107], v[92:93], v[92:93] op_sel_hi:[0,1]
	v_exp_f32_e32 v97, v91
	v_fmamk_f32 v91, v197, 0x3fb8aa3b, v209
	v_exp_f32_e32 v106, v91
	v_fmamk_f32 v91, v105, 0x3fb8aa3b, v209
	v_exp_f32_e32 v98, v91
	v_add_f32_e32 v99, v97, v101
	v_fmamk_f32 v91, v198, 0x3fb8aa3b, v209
	v_pk_add_f32 v[92:93], v[98:99], v[106:107]
	v_exp_f32_e32 v107, v91
	v_fmamk_f32 v91, v199, 0x3fb8aa3b, v209
	v_pk_add_f32 v[160:161], v[92:93], v[92:93] op_sel_hi:[0,1]
	v_exp_f32_e32 v99, v91
	v_fmamk_f32 v91, v200, 0x3fb8aa3b, v209
	v_exp_f32_e32 v160, v91
	v_fmamk_f32 v91, v201, 0x3fb8aa3b, v209
	v_exp_f32_e32 v104, v91
	v_add_f32_e32 v105, v99, v107
	v_fmamk_f32 v91, v202, 0x3fb8aa3b, v209
	v_pk_add_f32 v[92:93], v[104:105], v[160:161]
	v_exp_f32_e32 v161, v91
	v_fmamk_f32 v91, v203, 0x3fb8aa3b, v209
	v_pk_add_f32 v[164:165], v[92:93], v[92:93] op_sel_hi:[0,1]
	v_exp_f32_e32 v105, v91
	v_fmamk_f32 v91, v204, 0x3fb8aa3b, v209
	v_exp_f32_e32 v164, v91
	v_fmamk_f32 v91, v205, 0x3fb8aa3b, v209
	v_exp_f32_e32 v110, v91
	v_add_f32_e32 v111, v105, v161
	v_fmamk_f32 v91, v94, 0x3fb8aa3b, v209
	v_pk_add_f32 v[92:93], v[110:111], v[164:165]
	v_exp_f32_e32 v111, v91
	v_fmamk_f32 v91, v206, 0x3fb8aa3b, v209
	v_pk_add_f32 v[166:167], v[92:93], v[92:93] op_sel_hi:[0,1]
	v_exp_f32_e32 v109, v91
	v_fmamk_f32 v91, v207, 0x3fb8aa3b, v209
	v_fmac_f32_e32 v209, 0x3fb8aa3b, v208
	v_exp_f32_e32 v166, v91
	v_exp_f32_e32 v162, v209
	v_sub_f32_e32 v91, v195, v186
	v_mul_f32_e32 v91, 0x3fb8aa3b, v91
	v_add_f32_e32 v163, v109, v111
	v_exp_f32_e32 v94, v91
	v_pk_add_f32 v[92:93], v[162:163], v[166:167]
	v_cmp_neq_f32_e32 vcc, 1.0, v94
	v_pk_add_f32 v[92:93], v[92:93], v[92:93] op_sel:[0,1] op_sel_hi:[1,0]
	s_nop 0
	v_mov_b32_e32 v91, v92
	s_nop 1
	v_permlane32_swap_b32_e32 v92, v91
	s_cbranch_vccz .LBB0_1098
	v_pk_mul_f32 v[78:79], v[78:79], v[94:95] op_sel_hi:[1,0]
	v_pk_mul_f32 v[76:77], v[76:77], v[94:95] op_sel_hi:[1,0]
	v_pk_mul_f32 v[74:75], v[74:75], v[94:95] op_sel_hi:[1,0]
	v_pk_mul_f32 v[72:73], v[72:73], v[94:95] op_sel_hi:[1,0]
	v_pk_mul_f32 v[70:71], v[70:71], v[94:95] op_sel_hi:[1,0]
	v_pk_mul_f32 v[68:69], v[68:69], v[94:95] op_sel_hi:[1,0]
	v_pk_mul_f32 v[66:67], v[66:67], v[94:95] op_sel_hi:[1,0]
	v_pk_mul_f32 v[64:65], v[64:65], v[94:95] op_sel_hi:[1,0]
	v_pk_mul_f32 v[62:63], v[62:63], v[94:95] op_sel_hi:[1,0]
	v_pk_mul_f32 v[60:61], v[60:61], v[94:95] op_sel_hi:[1,0]
	v_pk_mul_f32 v[58:59], v[58:59], v[94:95] op_sel_hi:[1,0]
	v_pk_mul_f32 v[56:57], v[56:57], v[94:95] op_sel_hi:[1,0]
	v_pk_mul_f32 v[54:55], v[54:55], v[94:95] op_sel_hi:[1,0]
	v_pk_mul_f32 v[52:53], v[52:53], v[94:95] op_sel_hi:[1,0]
	v_pk_mul_f32 v[50:51], v[50:51], v[94:95] op_sel_hi:[1,0]
	v_pk_mul_f32 v[48:49], v[48:49], v[94:95] op_sel_hi:[1,0]
	v_pk_mul_f32 v[46:47], v[46:47], v[94:95] op_sel_hi:[1,0]
	v_pk_mul_f32 v[44:45], v[44:45], v[94:95] op_sel_hi:[1,0]
	v_pk_mul_f32 v[42:43], v[42:43], v[94:95] op_sel_hi:[1,0]
	v_pk_mul_f32 v[40:41], v[40:41], v[94:95] op_sel_hi:[1,0]
	v_pk_mul_f32 v[38:39], v[38:39], v[94:95] op_sel_hi:[1,0]
	v_pk_mul_f32 v[36:37], v[36:37], v[94:95] op_sel_hi:[1,0]
	v_pk_mul_f32 v[34:35], v[34:35], v[94:95] op_sel_hi:[1,0]
	v_pk_mul_f32 v[32:33], v[32:33], v[94:95] op_sel_hi:[1,0]
	v_pk_mul_f32 v[30:31], v[30:31], v[94:95] op_sel_hi:[1,0]
	v_pk_mul_f32 v[28:29], v[28:29], v[94:95] op_sel_hi:[1,0]
	v_pk_mul_f32 v[26:27], v[26:27], v[94:95] op_sel_hi:[1,0]
	v_pk_mul_f32 v[24:25], v[24:25], v[94:95] op_sel_hi:[1,0]
	v_pk_mul_f32 v[22:23], v[22:23], v[94:95] op_sel_hi:[1,0]
	v_pk_mul_f32 v[20:21], v[20:21], v[94:95] op_sel_hi:[1,0]
	v_pk_mul_f32 v[18:19], v[18:19], v[94:95] op_sel_hi:[1,0]
	v_pk_mul_f32 v[16:17], v[16:17], v[94:95] op_sel_hi:[1,0]
; __device__ __forceinline__ f16v mfma16(h8 a, h8 b, f16v c) { return __builtin_amdgcn_mfma_f32_32x32x16_f16(a, b, c, 0, 0, 0); }
; template <int EQK, int EV, bool PF, class KP, class SC>
; __device__ __forceinline__ void flash_core(f16v (&o)[EV / 32], float& m_run, float& l_run, const h8 (&qf)[EQK / 16],
;                                            int kt0, int kt1, const KP& kp, const SC& sc, char* smem) {
;     ...
;       h8 pf[4];
; #pragma unroll
;       for (int i = 0; i < 8; ++i) { pf[0][i] = (h16)p0[i]; pf[1][i] = (h16)p0[8 + i]; pf[2][i] = (h16)p1[i]; pf[3][i] = (h16)p1[8 + i]; }
; #pragma unroll
;       for (int et = 0; et < EV / 32; ++et) {
;         const h16* vb = sV + (et * 32 + l31) * VLD + hi * 4;
; #pragma unroll
;         for (int ks = 0; ks < 4; ++ks) {
;           h4 lo = *(const h4*)(vb + ks * 16), hh = *(const h4*)(vb + ks * 16 + 8);
;           h8 vf = {lo[0], lo[1], lo[2], lo[3], hh[0], hh[1], hh[2], hh[3]};
;           o[et] = mfma16(vf, pf[ks], o[et]);
;         }
;       }
;     }
;     if (PF) {
;       if (more) lstore(cur ^ 1);
;       __syncthreads();
;       cur ^= 1;
;     } else if (more) {
;       __syncthreads();
;       gload(kt + 1); lstore(0);
;       __syncthreads();
;     }
.LBB0_1098:
	v_lshl_add_u32 v93, v147, 1, s41
	v_add_u32_e32 v93, v253, v93
	v_cvt_pk_f16_f32 v195, v194, v108
	v_cvt_pk_f16_f32 v194, v193, v102
	v_cvt_pk_f16_f32 v193, v192, v96
	v_cvt_pk_f16_f32 v192, v191, v0
	v_add_u32_e32 v254, v93, v139
	v_cvt_pk_f16_f32 v103, v103, v100
	v_cvt_pk_f16_f32 v100, v95, v14
	v_cvt_pk_f16_f32 v167, v111, v166
	v_cvt_pk_f16_f32 v166, v161, v164
	v_cvt_pk_f16_f32 v164, v101, v106
	v_cvt_pk_f16_f32 v106, v105, v110
	v_cvt_pk_f16_f32 v105, v99, v104
	v_cvt_pk_f16_f32 v104, v97, v98
	ds_read_b128 v[96:99], v254 offset:13824
	s_waitcnt lgkmcnt(0)
	v_mfma_f32_32x32x16_f16 v[48:63], v[96:99], v[192:195], v[48:63]
	ds_read_b128 v[96:99], v254 offset:13856
	v_cvt_pk_f16_f32 v165, v107, v160
	v_cvt_pk_f16_f32 v102, v89, v90
	v_cvt_pk_f16_f32 v101, v15, v88
	v_cvt_pk_f16_f32 v107, v109, v162
	s_waitcnt lgkmcnt(0)
	v_mfma_f32_32x32x16_f16 v[48:63], v[96:99], v[164:167], v[48:63]
	ds_read_b128 v[96:99], v254 offset:13888
	ds_read_b128 v[196:199], v254 offset:9216
	s_xor_b32 s33, s33, 1
	s_mul_i32 s41, s33, 0x6c00
	s_mov_b64 s[8:9], 0x80
	s_waitcnt lgkmcnt(1)
	v_mfma_f32_32x32x16_f16 v[48:63], v[96:99], v[100:103], v[48:63]
	ds_read_b128 v[96:99], v254 offset:13920
	v_add_f32_e32 v14, v92, v91
	v_fmac_f32_e32 v14, v190, v94
	ds_read_b128 v[88:91], v254 offset:18528
	s_sub_i32 s2, s2, 64
	v_add_u32_e32 v148, s8, v148
	v_add_u32_e32 v150, s8, v150
	s_waitcnt lgkmcnt(1)
	v_mfma_f32_32x32x16_f16 v[48:63], v[96:99], v[104:107], v[48:63]
	ds_read_b128 v[96:99], v254 offset:18432
	v_add_u32_e32 v152, s8, v152
	v_add_u32_e32 v154, s8, v154
	s_mov_b64 s[8:9], 0x40000
	v_add_u32_e32 v156, s8, v156
	v_add_u32_e32 v158, s8, v158
	s_cmpk_lg_i32 s2, 0xf040
	v_mfma_f32_32x32x16_f16 v[64:79], v[196:199], v[192:195], v[64:79]
	ds_read_b128 v[196:199], v254 offset:9248
	s_waitcnt lgkmcnt(1)
	v_mfma_f32_32x32x16_f16 v[32:47], v[96:99], v[192:195], v[32:47]
	ds_read_b128 v[96:99], v254 offset:18464
	s_waitcnt lgkmcnt(1)
	v_mfma_f32_32x32x16_f16 v[64:79], v[196:199], v[164:167], v[64:79]
	ds_read_b128 v[196:199], v254 offset:9280
	s_waitcnt lgkmcnt(1)
	v_mfma_f32_32x32x16_f16 v[32:47], v[96:99], v[164:167], v[32:47]
	ds_read_b128 v[96:99], v254 offset:18496
	s_waitcnt lgkmcnt(1)
	v_mfma_f32_32x32x16_f16 v[64:79], v[196:199], v[100:103], v[64:79]
	ds_read_b128 v[196:199], v254 offset:9312
	s_waitcnt lgkmcnt(1)
	v_mfma_f32_32x32x16_f16 v[32:47], v[96:99], v[100:103], v[32:47]
	ds_read_b128 v[92:95], v254 offset:23040
	ds_read_b128 v[96:99], v254 offset:23072
	ds_read_b128 v[108:111], v254 offset:23104
	ds_read_b128 v[160:163], v254 offset:23136
	v_lshlrev_b32_e32 v0, 1, v172
	v_add3_u32 v0, s41, v0, v173
	s_waitcnt vmcnt(5)
	ds_write_b128 v0, v[6:9]
	v_lshlrev_b32_e32 v0, 1, v174
	v_add3_u32 v0, s41, v0, v175
	s_waitcnt vmcnt(4)
	ds_write_b128 v0, v[2:5]
	s_waitcnt lgkmcnt(5)
	v_mfma_f32_32x32x16_f16 v[16:31], v[92:95], v[192:195], v[16:31]
	v_lshlrev_b32_e32 v0, 1, v182
	v_add3_u32 v0, s41, v0, v146
	s_waitcnt vmcnt(3)
	v_add_u32_e32 v254, v252, v0
	ds_write2_b64 v254, v[128:129], v[130:131] offset1:2
	v_lshlrev_b32_e32 v0, 1, v183
	v_add3_u32 v0, s41, v0, v146
	s_waitcnt vmcnt(2)
	v_add_u32_e32 v255, v252, v0
	ds_write2_b64 v255, v[10:11], v[12:13] offset1:2
	v_lshlrev_b32_e32 v0, 1, v184
	s_waitcnt lgkmcnt(6)
	v_mfma_f32_32x32x16_f16 v[16:31], v[96:99], v[164:167], v[16:31]
	v_add3_u32 v0, s41, v0, v146
	s_waitcnt vmcnt(1)
	v_add_u32_e32 v254, v252, v0
	ds_write2_b64 v254, v[84:85], v[86:87] offset1:2
	v_lshlrev_b32_e32 v0, 1, v185
	v_add3_u32 v0, s41, v0, v146
	s_waitcnt vmcnt(0)
	v_add_u32_e32 v255, v252, v0
	ds_write2_b64 v255, v[80:81], v[82:83] offset1:2
	s_waitcnt lgkmcnt(0)
	s_barrier
	v_mfma_f32_32x32x16_f16 v[16:31], v[108:111], v[100:103], v[16:31]
	v_mfma_f32_32x32x16_f16 v[64:79], v[196:199], v[104:107], v[64:79]
	v_mfma_f32_32x32x16_f16 v[32:47], v[88:91], v[104:107], v[32:47]
	v_mfma_f32_32x32x16_f16 v[16:31], v[160:163], v[104:107], v[16:31]
	s_cbranch_scc0 .LBB0_1100
	v_mov_b32_e32 v190, v14
	s_branch .LBB0_1096

; __device__ __forceinline__ f16v mfma16(h8 a, h8 b, f16v c) { return __builtin_amdgcn_mfma_f32_32x32x16_f16(a, b, c, 0, 0, 0); }
;   __device__ __forceinline__ float tile_c0(int kt, int qslot, int hi) const { return (float)(q0 + qslot - kt * 64 - 4 * hi); }
;   __device__ __forceinline__ float apply(float pv, float c0, int jc) const { return fmaf(-slope, fabsf(c0 - (float)jc), pv); }
;   __device__ __forceinline__ float tile_c0(int kt, int qslot, int hi) const { return (float)(qslot + 64 - 64 * kt - 4 * hi); }
; template <int EQK, int EV, bool PF, class KP, class SC>
; __device__ __forceinline__ void flash_core(f16v (&o)[EV / 32], float& m_run, float& l_run, const h8 (&qf)[EQK / 16],
;                                            int kt0, int kt1, const KP& kp, const SC& sc, char* smem) {
;     ...
;     if (!sc.wave_skip(kt, wid)) {
;       const h16* sK = base + (PF ? cur : 0) * BUFH;
;       const h16* sV = sK + 64 * KLD;
;       f16v p0, p1;
; #pragma unroll
;       for (int r = 0; r < 16; ++r) { p0[r] = 0.f; p1[r] = 0.f; }
; #pragma unroll
;       for (int d0 = 0; d0 < EQK / 16; ++d0) {
;         h8 a0 = *(const h8*)(sK + l31 * KLD + d0 * 16 + hi * 8);
;         h8 a1 = *(const h8*)(sK + (32 + l31) * KLD + d0 * 16 + hi * 8);
;         p0 = mfma16(a0, qf[d0], p0);
;         p1 = mfma16(a1, qf[d0], p1);
;       }
;       const float c0 = sc.tile_c0(kt, qslot, hi);
;       float mx = -1e30f;
; #pragma unroll
;       for (int r = 0; r < 16; ++r) {
;         const int jc = (r & 3) + 8 * (r >> 2);
;         p0[r] = sc.apply(p0[r], c0, jc);
;         p1[r] = sc.apply(p1[r], c0, 32 + jc);
;         mx = fmaxf(mx, fmaxf(p0[r], p1[r]));
;       }
.LBB0_1103:
	s_mul_i32 s15, s14, 0x6c00
	v_lshlrev_b32_e32 v188, 1, v145
	v_add3_u32 v0, s15, v188, v187
	ds_read_b128 v[2:5], v0
	ds_read_b128 v[6:9], v0 offset:32
	v_mov_b32_e32 v194, v184
	s_waitcnt lgkmcnt(1)
	v_mfma_f32_32x32x16_f16 v[80:95], v[2:5], v[124:127], 0
	ds_read_b128 v[2:5], v0 offset:4608
	ds_read_b128 v[10:13], v0 offset:4640
	s_waitcnt lgkmcnt(1)
	v_mfma_f32_32x32x16_f16 v[96:111], v[2:5], v[124:127], 0
	v_mfma_f32_32x32x16_f16 v[80:95], v[6:9], v[120:123], v[80:95]
	s_waitcnt lgkmcnt(0)
	v_mfma_f32_32x32x16_f16 v[96:111], v[10:13], v[120:123], v[96:111]
	ds_read_b128 v[2:5], v0 offset:64
	ds_read_b128 v[10:13], v0 offset:96
	s_waitcnt lgkmcnt(1)
	v_mfma_f32_32x32x16_f16 v[80:95], v[2:5], v[116:119], v[80:95]
	ds_read_b128 v[2:5], v0 offset:4672
	ds_read_b128 v[158:161], v0 offset:4704
	v_add_u32_e32 v0, s2, v186
	v_cvt_f32_i32_e32 v0, v0
	s_waitcnt lgkmcnt(1)
	v_mfma_f32_32x32x16_f16 v[96:111], v[2:5], v[116:119], v[96:111]
	global_load_dwordx4 v[6:9], v156, s[58:59]
	s_nop 0
	global_load_dwordx4 v[2:5], v154, s[58:59]
	s_waitcnt lgkmcnt(0)
	v_mfma_f32_32x32x16_f16 v[96:111], v[158:161], v[112:115], v[96:111]
	v_mfma_f32_32x32x16_f16 v[80:95], v[10:13], v[112:115], v[80:95]
	global_load_dwordx4 v[128:131], v152, s[58:59]
	s_nop 0
	global_load_dwordx4 v[10:13], v150, s[58:59]
	s_add_i32 vcc_lo, s2, s47
	s_cmp_gt_i32 vcc_lo, 63
	s_cbranch_scc1 .Lda2_left
	s_cmp_lt_i32 vcc_lo, 0xffffff81
	s_cbranch_scc1 .Lda2_right
	v_mov_b32_e32 v249, 0
	v_add_f32_e32 v15, 0xc2000000, v0
	s_nop 5
	v_fma_f32 v15, -v137, |v15|, v96
	v_add_f32_e32 v96, -1.0, v0
	v_fma_f32 v81, -v137, |v96|, v81
	v_add_f32_e32 v96, 0xc2040000, v0
	v_fma_f32 v14, -v137, |v0|, v80
	v_fma_f32 v96, -v137, |v96|, v97
	v_max_f32_e32 v80, v14, v15
	v_max_f32_e32 v97, v81, v96
	v_max3_f32 v80, v80, s3, v97
	v_add_f32_e32 v97, -2.0, v0
	v_fma_f32 v158, -v137, |v97|, v82
	v_add_f32_e32 v97, 0xc0400000, v0
	v_add_f32_e32 v82, 0xc2080000, v0
	v_fma_f32 v159, -v137, |v97|, v83
	v_add_f32_e32 v83, 0xc20c0000, v0
	v_fma_f32 v98, -v137, |v82|, v98
	v_fma_f32 v99, -v137, |v83|, v99
	v_max_f32_e32 v82, v158, v98
	v_max_f32_e32 v83, v159, v99
	v_max3_f32 v80, v80, v82, v83
	v_add_f32_e32 v82, 0xc1000000, v0
	v_add_f32_e32 v83, 0xc1100000, v0
	v_fma_f32 v160, -v137, |v82|, v84
	v_add_f32_e32 v82, 0xc2200000, v0
	v_fma_f32 v161, -v137, |v83|, v85
	v_add_f32_e32 v83, 0xc2240000, v0
	v_fma_f32 v100, -v137, |v82|, v100
	v_fma_f32 v101, -v137, |v83|, v101
	v_max_f32_e32 v82, v160, v100
	v_max_f32_e32 v83, v161, v101
	v_max3_f32 v80, v80, v82, v83
	v_add_f32_e32 v82, 0xc1200000, v0
	v_add_f32_e32 v83, 0xc1300000, v0
	v_fma_f32 v162, -v137, |v82|, v86
	v_add_f32_e32 v82, 0xc2280000, v0
	v_fma_f32 v164, -v137, |v83|, v87
	v_add_f32_e32 v83, 0xc22c0000, v0
	v_fma_f32 v163, -v137, |v82|, v102
	v_fma_f32 v165, -v137, |v83|, v103
	v_max_f32_e32 v82, v162, v163
	v_max_f32_e32 v83, v164, v165
	v_max3_f32 v80, v80, v82, v83
	v_add_f32_e32 v82, 0xc1800000, v0
	v_add_f32_e32 v83, 0xc1880000, v0
	v_fma_f32 v195, -v137, |v82|, v88
	v_add_f32_e32 v82, 0xc2400000, v0
	v_fma_f32 v196, -v137, |v83|, v89
	v_add_f32_e32 v83, 0xc2440000, v0
	v_fma_f32 v104, -v137, |v82|, v104
	v_fma_f32 v105, -v137, |v83|, v105
	v_max_f32_e32 v82, v195, v104
	v_max_f32_e32 v83, v196, v105
	v_max3_f32 v80, v80, v82, v83
	v_add_f32_e32 v82, 0xc1900000, v0
	v_add_f32_e32 v83, 0xc1980000, v0
	v_fma_f32 v197, -v137, |v82|, v90
	v_add_f32_e32 v82, 0xc2480000, v0
	v_fma_f32 v199, -v137, |v83|, v91
	v_add_f32_e32 v83, 0xc24c0000, v0
	v_fma_f32 v198, -v137, |v82|, v106
	v_fma_f32 v200, -v137, |v83|, v107
	v_max_f32_e32 v82, v197, v198
	v_max_f32_e32 v83, v199, v200
	v_max3_f32 v80, v80, v82, v83
	v_add_f32_e32 v82, 0xc1c00000, v0
	v_add_f32_e32 v83, 0xc1c80000, v0
	v_fma_f32 v201, -v137, |v82|, v92
	v_add_f32_e32 v82, 0xc2600000, v0
	v_fma_f32 v203, -v137, |v83|, v93
	v_add_f32_e32 v83, 0xc2640000, v0
	v_fma_f32 v202, -v137, |v82|, v108
	v_fma_f32 v204, -v137, |v83|, v109
	v_max_f32_e32 v82, v201, v202
	v_max_f32_e32 v83, v203, v204
	v_max3_f32 v80, v80, v82, v83
	v_add_f32_e32 v82, 0xc1d00000, v0
	v_fma_f32 v94, -v137, |v82|, v94
	v_add_f32_e32 v82, 0xc2680000, v0
	v_add_f32_e32 v83, 0xc1d80000, v0
	v_add_f32_e32 v0, 0xc26c0000, v0
	v_fma_f32 v205, -v137, |v82|, v110
	v_fma_f32 v206, -v137, |v83|, v95
	v_fma_f32 v207, -v137, |v0|, v111
	v_max_f32_e32 v82, v94, v205
	v_max_f32_e32 v0, v206, v207
	v_max3_f32 v0, v80, v82, v0
	s_branch .Lda2_join

; template <int EQK, int EV, bool PF, class KP, class SC>
; __device__ __forceinline__ void flash_core(f16v (&o)[EV / 32], float& m_run, float& l_run, const h8 (&qf)[EQK / 16],
;                                            int kt0, int kt1, const KP& kp, const SC& sc, char* smem) {
;     ...
;     for (int i = 0; i < NKC; ++i) { int c = tid + 256 * i, row = c / KCH, kc = (c - row * KCH) * 8; rk[i] = *(const h8*)(kp.kptr(kt, row) + kc); }
; #pragma unroll
;     for (int i = 0; i < NVC; ++i) { int c = tid + 256 * i, e = c >> 3, kc = (c & 7) * 8; rv[i] = *(const h8*)(kp.vptr(kt, e) + kc); }
;     ...
;       mx = xhalf_max(mx);
;       const float m_new = fmaxf(m_run, mx);
;       const float alpha = __builtin_amdgcn_exp2f((m_run - m_new) * L2E);
;       const float mneg = -m_new * L2E;
;       float ps = 0.f;
; #pragma unroll
;       for (int r = 0; r < 16; ++r) {
;         p0[r] = __builtin_amdgcn_exp2f(fmaf(p0[r], L2E, mneg));
;         p1[r] = __builtin_amdgcn_exp2f(fmaf(p1[r], L2E, mneg));
;         ps += p0[r] + p1[r];
;       }
;       ps = xhalf_sum(ps);
;       l_run = l_run * alpha + ps;
;       m_run = m_new;
;       if (__any(alpha != 1.f)) {
; #pragma unroll
;         for (int et = 0; et < EV / 32; ++et)
; #pragma unroll
;           for (int r = 0; r < 16; ++r) o[et][r] *= alpha;
;       }
.Lda2_join:
	v_add_f32_e32 v0, v249, v0
	v_mov_b32_e32 v80, v0
	s_nop 1
	v_permlane32_swap_b32_e32 v0, v80
	v_max3_f32 v184, v194, v0, v80
	v_sub_f32_e32 v208, v249, v184
	v_mul_f32_e32 v208, 0x3fb8aa3b, v208
	v_fmamk_f32 v0, v14, 0x3fb8aa3b, v208
	v_exp_f32_e32 v190, v0
	v_fmamk_f32 v0, v15, 0x3fb8aa3b, v208
	v_exp_f32_e32 v95, v0
	v_fmamk_f32 v0, v81, 0x3fb8aa3b, v208
	v_fmamk_f32 v14, v96, 0x3fb8aa3b, v208
	v_exp_f32_e32 v0, v0
	v_exp_f32_e32 v14, v14
	v_add_f32_e32 v15, v95, v190
	v_pk_add_f32 v[84:85], v[14:15], v[0:1]
	v_fmamk_f32 v15, v158, 0x3fb8aa3b, v208
	v_pk_add_f32 v[96:97], v[84:85], v[84:85] op_sel_hi:[0,1]
	v_fmamk_f32 v84, v159, 0x3fb8aa3b, v208
	v_exp_f32_e32 v96, v84
	v_fmamk_f32 v84, v99, 0x3fb8aa3b, v208
	v_exp_f32_e32 v88, v84
	global_load_dwordx4 v[84:87], v148, s[58:59]
	s_nop 0
	global_load_dwordx4 v[80:83], v146, s[58:59]
	v_exp_f32_e32 v191, v15
	v_fmamk_f32 v15, v98, 0x3fb8aa3b, v208
	v_exp_f32_e32 v15, v15
	s_nop 0
	v_add_f32_e32 v89, v15, v191
	v_pk_add_f32 v[90:91], v[88:89], v[96:97]
	v_fmamk_f32 v89, v160, 0x3fb8aa3b, v208
	v_pk_add_f32 v[102:103], v[90:91], v[90:91] op_sel_hi:[0,1]
	v_exp_f32_e32 v192, v89
	v_fmamk_f32 v89, v100, 0x3fb8aa3b, v208
	v_fmamk_f32 v90, v161, 0x3fb8aa3b, v208
	v_exp_f32_e32 v89, v89
	v_exp_f32_e32 v102, v90
	v_fmamk_f32 v90, v101, 0x3fb8aa3b, v208
	v_exp_f32_e32 v90, v90
	v_add_f32_e32 v91, v89, v192
	v_pk_add_f32 v[92:93], v[90:91], v[102:103]
	v_fmamk_f32 v91, v162, 0x3fb8aa3b, v208
	v_exp_f32_e32 v193, v91
	v_fmamk_f32 v91, v163, 0x3fb8aa3b, v208
	v_pk_add_f32 v[108:109], v[92:93], v[92:93] op_sel_hi:[0,1]
	v_exp_f32_e32 v103, v91
	v_fmamk_f32 v91, v164, 0x3fb8aa3b, v208
	v_exp_f32_e32 v108, v91
	v_fmamk_f32 v91, v165, 0x3fb8aa3b, v208
	v_exp_f32_e32 v100, v91
	v_add_f32_e32 v101, v103, v193
	v_fmamk_f32 v91, v195, 0x3fb8aa3b, v208
	v_pk_add_f32 v[92:93], v[100:101], v[108:109]
	v_exp_f32_e32 v101, v91
	v_fmamk_f32 v91, v104, 0x3fb8aa3b, v208
	v_pk_add_f32 v[106:107], v[92:93], v[92:93] op_sel_hi:[0,1]
	v_exp_f32_e32 v97, v91
	v_fmamk_f32 v91, v196, 0x3fb8aa3b, v208
	v_exp_f32_e32 v106, v91
	v_fmamk_f32 v91, v105, 0x3fb8aa3b, v208
	v_exp_f32_e32 v98, v91
	v_add_f32_e32 v99, v97, v101
	v_fmamk_f32 v91, v197, 0x3fb8aa3b, v208
	v_pk_add_f32 v[92:93], v[98:99], v[106:107]
	v_exp_f32_e32 v107, v91
	v_fmamk_f32 v91, v198, 0x3fb8aa3b, v208
	v_pk_add_f32 v[158:159], v[92:93], v[92:93] op_sel_hi:[0,1]
	v_exp_f32_e32 v99, v91
	v_fmamk_f32 v91, v199, 0x3fb8aa3b, v208
	v_exp_f32_e32 v158, v91
	v_fmamk_f32 v91, v200, 0x3fb8aa3b, v208
	v_exp_f32_e32 v104, v91
	v_add_f32_e32 v105, v99, v107
	v_fmamk_f32 v91, v201, 0x3fb8aa3b, v208
	v_pk_add_f32 v[92:93], v[104:105], v[158:159]
	v_exp_f32_e32 v159, v91
	v_fmamk_f32 v91, v202, 0x3fb8aa3b, v208
	v_pk_add_f32 v[162:163], v[92:93], v[92:93] op_sel_hi:[0,1]
	v_exp_f32_e32 v105, v91
	v_fmamk_f32 v91, v203, 0x3fb8aa3b, v208
	v_exp_f32_e32 v162, v91
	v_fmamk_f32 v91, v204, 0x3fb8aa3b, v208
	v_exp_f32_e32 v110, v91
	v_add_f32_e32 v111, v105, v159
	v_fmamk_f32 v91, v94, 0x3fb8aa3b, v208
	v_pk_add_f32 v[92:93], v[110:111], v[162:163]
	v_exp_f32_e32 v111, v91
	v_fmamk_f32 v91, v205, 0x3fb8aa3b, v208
	v_pk_add_f32 v[164:165], v[92:93], v[92:93] op_sel_hi:[0,1]
	v_exp_f32_e32 v109, v91
	v_fmamk_f32 v91, v206, 0x3fb8aa3b, v208
	v_fmac_f32_e32 v208, 0x3fb8aa3b, v207
	v_exp_f32_e32 v164, v91
	v_exp_f32_e32 v160, v208
	v_sub_f32_e32 v91, v194, v184
	v_mul_f32_e32 v91, 0x3fb8aa3b, v91
	v_add_f32_e32 v161, v109, v111
	v_exp_f32_e32 v94, v91
	v_pk_add_f32 v[92:93], v[160:161], v[164:165]
	v_cmp_neq_f32_e32 vcc, 1.0, v94
	v_pk_add_f32 v[92:93], v[92:93], v[92:93] op_sel:[0,1] op_sel_hi:[1,0]
	s_nop 0
	v_mov_b32_e32 v91, v92
	s_nop 1
	v_permlane32_swap_b32_e32 v92, v91
	s_cbranch_vccz .LBB0_1105
	v_pk_mul_f32 v[78:79], v[78:79], v[94:95] op_sel_hi:[1,0]
	v_pk_mul_f32 v[76:77], v[76:77], v[94:95] op_sel_hi:[1,0]
	v_pk_mul_f32 v[74:75], v[74:75], v[94:95] op_sel_hi:[1,0]
	v_pk_mul_f32 v[72:73], v[72:73], v[94:95] op_sel_hi:[1,0]
	v_pk_mul_f32 v[70:71], v[70:71], v[94:95] op_sel_hi:[1,0]
	v_pk_mul_f32 v[68:69], v[68:69], v[94:95] op_sel_hi:[1,0]
	v_pk_mul_f32 v[66:67], v[66:67], v[94:95] op_sel_hi:[1,0]
	v_pk_mul_f32 v[64:65], v[64:65], v[94:95] op_sel_hi:[1,0]
	v_pk_mul_f32 v[62:63], v[62:63], v[94:95] op_sel_hi:[1,0]
	v_pk_mul_f32 v[60:61], v[60:61], v[94:95] op_sel_hi:[1,0]
	v_pk_mul_f32 v[58:59], v[58:59], v[94:95] op_sel_hi:[1,0]
	v_pk_mul_f32 v[56:57], v[56:57], v[94:95] op_sel_hi:[1,0]
	v_pk_mul_f32 v[54:55], v[54:55], v[94:95] op_sel_hi:[1,0]
	v_pk_mul_f32 v[52:53], v[52:53], v[94:95] op_sel_hi:[1,0]
	v_pk_mul_f32 v[50:51], v[50:51], v[94:95] op_sel_hi:[1,0]
	v_pk_mul_f32 v[48:49], v[48:49], v[94:95] op_sel_hi:[1,0]
	v_pk_mul_f32 v[46:47], v[46:47], v[94:95] op_sel_hi:[1,0]
	v_pk_mul_f32 v[44:45], v[44:45], v[94:95] op_sel_hi:[1,0]
	v_pk_mul_f32 v[42:43], v[42:43], v[94:95] op_sel_hi:[1,0]
	v_pk_mul_f32 v[40:41], v[40:41], v[94:95] op_sel_hi:[1,0]
	v_pk_mul_f32 v[38:39], v[38:39], v[94:95] op_sel_hi:[1,0]
	v_pk_mul_f32 v[36:37], v[36:37], v[94:95] op_sel_hi:[1,0]
	v_pk_mul_f32 v[34:35], v[34:35], v[94:95] op_sel_hi:[1,0]
	v_pk_mul_f32 v[32:33], v[32:33], v[94:95] op_sel_hi:[1,0]
	v_pk_mul_f32 v[30:31], v[30:31], v[94:95] op_sel_hi:[1,0]
	v_pk_mul_f32 v[28:29], v[28:29], v[94:95] op_sel_hi:[1,0]
	v_pk_mul_f32 v[26:27], v[26:27], v[94:95] op_sel_hi:[1,0]
	v_pk_mul_f32 v[24:25], v[24:25], v[94:95] op_sel_hi:[1,0]
	v_pk_mul_f32 v[22:23], v[22:23], v[94:95] op_sel_hi:[1,0]
	v_pk_mul_f32 v[20:21], v[20:21], v[94:95] op_sel_hi:[1,0]
	v_pk_mul_f32 v[18:19], v[18:19], v[94:95] op_sel_hi:[1,0]
	v_pk_mul_f32 v[16:17], v[16:17], v[94:95] op_sel_hi:[1,0]
; __device__ __forceinline__ f16v mfma16(h8 a, h8 b, f16v c) { return __builtin_amdgcn_mfma_f32_32x32x16_f16(a, b, c, 0, 0, 0); }
; template <int EQK, int EV, bool PF, class KP, class SC>
; __device__ __forceinline__ void flash_core(f16v (&o)[EV / 32], float& m_run, float& l_run, const h8 (&qf)[EQK / 16],
;                                            int kt0, int kt1, const KP& kp, const SC& sc, char* smem) {
;     ...
;       h8 pf[4];
; #pragma unroll
;       for (int i = 0; i < 8; ++i) { pf[0][i] = (h16)p0[i]; pf[1][i] = (h16)p0[8 + i]; pf[2][i] = (h16)p1[i]; pf[3][i] = (h16)p1[8 + i]; }
; #pragma unroll
;       for (int et = 0; et < EV / 32; ++et) {
;         const h16* vb = sV + (et * 32 + l31) * VLD + hi * 4;
; #pragma unroll
;         for (int ks = 0; ks < 4; ++ks) {
;           h4 lo = *(const h4*)(vb + ks * 16), hh = *(const h4*)(vb + ks * 16 + 8);
;           h8 vf = {lo[0], lo[1], lo[2], lo[3], hh[0], hh[1], hh[2], hh[3]};
;           o[et] = mfma16(vf, pf[ks], o[et]);
;         }
;       }
;     }
;     if (PF) {
;       if (more) lstore(cur ^ 1);
;       __syncthreads();
;       cur ^= 1;
;     } else if (more) {
;       __syncthreads();
;       gload(kt + 1); lstore(0);
;       __syncthreads();
;     }
.LBB0_1105:
	v_lshl_add_u32 v93, v166, 1, s15
	v_add_u32_e32 v93, v253, v93
	v_cvt_pk_f16_f32 v190, v190, v0
	v_add_u32_e32 v254, v93, v139
	v_cvt_pk_f16_f32 v103, v103, v100
	v_cvt_pk_f16_f32 v100, v95, v14
	v_cvt_pk_f16_f32 v191, v191, v96
	v_cvt_pk_f16_f32 v165, v111, v164
	v_cvt_pk_f16_f32 v164, v159, v162
	v_cvt_pk_f16_f32 v162, v101, v106
	v_cvt_pk_f16_f32 v106, v105, v110
	v_cvt_pk_f16_f32 v105, v99, v104
	v_cvt_pk_f16_f32 v104, v97, v98
	ds_read_b128 v[96:99], v254 offset:13824
	v_cvt_pk_f16_f32 v193, v193, v108
	v_cvt_pk_f16_f32 v192, v192, v102
	v_cvt_pk_f16_f32 v163, v107, v158
	v_cvt_pk_f16_f32 v102, v89, v90
	s_waitcnt lgkmcnt(0)
	v_mfma_f32_32x32x16_f16 v[48:63], v[96:99], v[190:193], v[48:63]
	ds_read_b128 v[96:99], v254 offset:13856
	v_cvt_pk_f16_f32 v101, v15, v88
	v_cvt_pk_f16_f32 v107, v109, v160
	ds_read_b128 v[194:197], v254 offset:9216
	s_waitcnt lgkmcnt(1)
	v_mfma_f32_32x32x16_f16 v[48:63], v[96:99], v[162:165], v[48:63]
	ds_read_b128 v[96:99], v254 offset:13888
	s_xor_b32 s14, s14, 1
	s_mul_i32 s15, s14, 0x6c00
	s_sub_i32 s2, s2, 64
	s_mov_b64 s[8:9], 0x40000
	v_lshl_add_u64 v[146:147], v[146:147], 0, s[40:41]
	s_waitcnt lgkmcnt(0)
	v_mfma_f32_32x32x16_f16 v[48:63], v[96:99], v[100:103], v[48:63]
	ds_read_b128 v[96:99], v254 offset:13920
	v_add_f32_e32 v14, v92, v91
	v_fmac_f32_e32 v14, v189, v94
	ds_read_b128 v[88:91], v254 offset:18528
	v_lshl_add_u64 v[148:149], v[148:149], 0, s[40:41]
	v_lshl_add_u64 v[150:151], v[150:151], 0, s[40:41]
	v_lshl_add_u64 v[152:153], v[152:153], 0, s[40:41]
	s_waitcnt lgkmcnt(1)
	v_mfma_f32_32x32x16_f16 v[48:63], v[96:99], v[104:107], v[48:63]
	ds_read_b128 v[96:99], v254 offset:18432
	v_add_u32_e32 v154, s8, v154
	v_add_u32_e32 v156, s8, v156
	s_cmpk_lg_i32 s2, 0xf040
	v_mfma_f32_32x32x16_f16 v[64:79], v[194:197], v[190:193], v[64:79]
	ds_read_b128 v[194:197], v254 offset:9248
	s_waitcnt lgkmcnt(1)
	v_mfma_f32_32x32x16_f16 v[32:47], v[96:99], v[190:193], v[32:47]
	ds_read_b128 v[96:99], v254 offset:18464
	s_waitcnt lgkmcnt(1)
	v_mfma_f32_32x32x16_f16 v[64:79], v[194:197], v[162:165], v[64:79]
	ds_read_b128 v[194:197], v254 offset:9280
	s_waitcnt lgkmcnt(1)
	v_mfma_f32_32x32x16_f16 v[32:47], v[96:99], v[162:165], v[32:47]
	ds_read_b128 v[96:99], v254 offset:18496
	s_waitcnt lgkmcnt(1)
	v_mfma_f32_32x32x16_f16 v[64:79], v[194:197], v[100:103], v[64:79]
	ds_read_b128 v[194:197], v254 offset:9312
	s_waitcnt lgkmcnt(1)
	v_mfma_f32_32x32x16_f16 v[32:47], v[96:99], v[100:103], v[32:47]
	ds_read_b128 v[92:95], v254 offset:23040
	ds_read_b128 v[96:99], v254 offset:23072
	ds_read_b128 v[108:111], v254 offset:23104
	ds_read_b128 v[158:161], v254 offset:23136
	v_lshlrev_b32_e32 v0, 1, v171
	v_add3_u32 v0, s15, v0, v172
	s_waitcnt vmcnt(5)
	ds_write_b128 v0, v[6:9]
	v_lshlrev_b32_e32 v0, 1, v173
	v_add3_u32 v0, s15, v0, v174
	s_waitcnt vmcnt(4)
	ds_write_b128 v0, v[2:5]
	s_waitcnt lgkmcnt(5)
	v_mfma_f32_32x32x16_f16 v[16:31], v[92:95], v[190:193], v[16:31]
	v_lshlrev_b32_e32 v0, 1, v175
	v_add3_u32 v0, s15, v0, v144
	s_waitcnt vmcnt(3)
	v_add_u32_e32 v254, v252, v0
	ds_write2_b64 v254, v[128:129], v[130:131] offset1:2
	v_lshlrev_b32_e32 v0, 1, v182
	v_add3_u32 v0, s15, v0, v144
	s_waitcnt vmcnt(2)
	v_add_u32_e32 v255, v252, v0
	ds_write2_b64 v255, v[10:11], v[12:13] offset1:2
	v_lshlrev_b32_e32 v0, 1, v183
	s_waitcnt lgkmcnt(6)
	v_mfma_f32_32x32x16_f16 v[16:31], v[96:99], v[162:165], v[16:31]
	v_add3_u32 v0, s15, v0, v144
	s_waitcnt vmcnt(1)
	v_add_u32_e32 v254, v252, v0
	ds_write2_b64 v254, v[84:85], v[86:87] offset1:2
	v_lshlrev_b32_e32 v0, 1, v185
	v_add3_u32 v0, s15, v0, v144
	s_waitcnt vmcnt(0)
	v_add_u32_e32 v255, v252, v0
	ds_write2_b64 v255, v[80:81], v[82:83] offset1:2
	s_waitcnt lgkmcnt(0)
	s_barrier
	v_mfma_f32_32x32x16_f16 v[16:31], v[108:111], v[100:103], v[16:31]
	v_mfma_f32_32x32x16_f16 v[64:79], v[194:197], v[104:107], v[64:79]
	v_mfma_f32_32x32x16_f16 v[32:47], v[88:91], v[104:107], v[32:47]
	v_mfma_f32_32x32x16_f16 v[16:31], v[158:161], v[104:107], v[16:31]
	s_cbranch_scc0 .LBB0_1107
	v_mov_b32_e32 v189, v14
	s_branch .LBB0_1103
